# P1 gate tiles: weight tile staged once per workgroup in LDS, 17 tiles on each idle-round workgroup
# baseline (speedup 1.0000x reference)
; __device__ __forceinline__ f32x4 mfma16(h16x8 a, h16x8 b, f32x4 c) { return __builtin_amdgcn_mfma_f32_16x16x32_f16(a, b, c, 0, 0, 0); }
; template <int MODE>
; __device__ __forceinline__ void skinny(const Params& p, const h16* A, int lda, int row0, int nrt, const h16* Bt, int K, int nct) {
;     ...
;     const int gw = blockIdx.x * 8 + wave, ngw = gridDim.x * 8;
;     unsigned char* ws = p.ws;
;     for (int task = gw; task < nrt * nct; task += ngw) {
;         const int rt = task % nrt, ct = task / nrt;
;         const h16* ap = A + (size_t)(row0 + rt * 16 + fr) * lda + fq * 8;
;         const h16* bp = Bt + (size_t)(ct * 16 + fr) * K + fq * 8;
;         f32x4 acc = {0.f, 0.f, 0.f, 0.f};
; #pragma unroll 8
;         for (int k = 0; k < K; k += 32) { const h16x8 a = *(const h16x8*)(ap + k); const h16x8 b = *(const h16x8*)(bp + k); acc = mfma16(b, a, acc); }
.LBB0_89:
	v_addc_co_u32_e64 v10, vcc, v131, v133, s[6:7]
	s_movk_i32 s0, 0x408
	v_bfe_u32 v144, v132, 4, 2
	v_and_b32_e32 v131, 15, v132
	s_lshl_b32 s88, s33, 3
	v_and_b32_e32 v56, 7, v130
	v_lshrrev_b32_e32 v57, 3, v130
	v_add_u32_e32 v54, 0x341, v57
	v_cmp_eq_u32_e64 s[98:99], 0, v56
	v_cmp_gt_u32_e32 vcc, 0xc7, v57
	s_and_b64 vcc, vcc, s[98:99]
	v_mov_b32_e32 v59, 0x7fff0000
	v_cndmask_b32_e32 v54, v59, v54, vcc
	v_add_u32_e32 v55, 1, v54
	v_subrev_u32_e32 v58, 0xcf, v57
	v_mul_u32_u24_e32 v58, 17, v58
	v_add_u32_e32 v59, v58, v56
	v_add_u32_e32 v58, 17, v58
	v_cmp_lt_u32_e32 vcc, 0xce, v57
	s_nop 1
	v_cndmask_b32_e32 v54, v54, v59, vcc
	v_cndmask_b32_e32 v55, v55, v58, vcc
	v_min_u32_e32 v55, 0x408, v55
	v_mov_b32_e32 v56, 8
	s_cmpk_eq_i32 s33, 0x100
	s_cselect_b64 s[98:99], -1, 0
	v_mov_b32_e32 v58, 0x408
	v_mov_b32_e32 v59, s88
	v_cndmask_b32_e64 v54, v130, v54, s[98:99]
	v_cndmask_b32_e64 v55, v58, v55, s[98:99]
	v_cndmask_b32_e64 v56, v59, v56, s[98:99]
	s_cmpk_lg_i32 s33, 0x100
	s_cbranch_scc1 .Lsk1_nostage
	v_lshrrev_b32_e32 v60, 6, v132
	v_and_b32_e32 v61, 63, v132
	v_readfirstlane_b32 s97, v60
	v_lshlrev_b32_e32 v61, 4, v61
	v_lshlrev_b32_e32 v62, 11, v131
	v_lshl_add_u32 v62, v144, 4, v62
	s_lshl_b32 s98, s97, 8
	s_lshl_b32 s99, s97, 12
	s_add_u32 s98, s98, 0x780000
	v_add_u32_e32 v62, s98, v62
	v_mov_b32_e32 v63, 0
	v_lshl_add_u64 v[62:63], s[82:83], 0, v[62:63]
	s_add_i32 m0, s99, 0x0
	s_nop 0
	global_load_lds_dwordx4 v[62:63], off
	v_add_co_u32_e32 v62, vcc, 64, v62
	s_nop 1
	v_addc_co_u32_e32 v63, vcc, 0, v63, vcc
	s_add_i32 m0, s99, 0x400
	s_nop 0
	global_load_lds_dwordx4 v[62:63], off
	v_add_co_u32_e32 v62, vcc, 64, v62
	s_nop 1
	v_addc_co_u32_e32 v63, vcc, 0, v63, vcc
	s_add_i32 m0, s99, 0x800
	s_nop 0
	global_load_lds_dwordx4 v[62:63], off
	v_add_co_u32_e32 v62, vcc, 64, v62
	s_nop 1
	v_addc_co_u32_e32 v63, vcc, 0, v63, vcc
	s_add_i32 m0, s99, 0xc00
	s_nop 0
	global_load_lds_dwordx4 v[62:63], off
	s_waitcnt vmcnt(0)
	s_barrier
.Lsk1_nostage:
	v_cmp_lt_i32_e32 vcc, v54, v55
	v_lshlrev_b32_e32 v138, 2, v144
	v_lshlrev_b32_e32 v140, 4, v144
	s_and_saveexec_b64 s[0:1], vcc
	s_cbranch_execz .LBB0_94
	s_add_u32 s6, s82, 0x19c8000
	s_movk_i32 s24, 0xffe0
	s_movk_i32 s26, 0xffe4
	s_movk_i32 s28, 0xffe8
	s_movk_i32 s30, 0xffec
	s_addc_u32 s7, s83, 0
	v_mov_b32_e32 v141, 0
	s_mov_b64 s[8:9], 0
	s_mov_b32 s34, 0xfe03f81
	s_mov_b64 s[10:11], 0x200
	s_mov_b32 s25, -1
	s_mov_b32 s27, -1
	s_mov_b32 s29, -1
	s_mov_b32 s31, -1
	s_movk_i32 s35, 0x407
	v_mov_b32_e32 v11, v54

; __device__ __forceinline__ f32x4 mfma16(h16x8 a, h16x8 b, f32x4 c) { return __builtin_amdgcn_mfma_f32_16x16x32_f16(a, b, c, 0, 0, 0); }
; template <int MODE>
; __device__ __forceinline__ void skinny(const Params& p, const h16* A, int lda, int row0, int nrt, const h16* Bt, int K, int nct) {
;     ...
;         const h16* ap = A + (size_t)(row0 + rt * 16 + fr) * lda + fq * 8;
;         const h16* bp = Bt + (size_t)(ct * 16 + fr) * K + fq * 8;
;         f32x4 acc = {0.f, 0.f, 0.f, 0.f};
; #pragma unroll 8
;         for (int k = 0; k < K; k += 32) { const h16x8 a = *(const h16x8*)(ap + k); const h16x8 b = *(const h16x8*)(bp + k); acc = mfma16(b, a, acc); }
.LBB0_92:
	s_cmpk_lg_i32 s33, 0x100
	s_cbranch_scc1 .Lsk1_orig
	v_lshl_add_u64 v[14:15], v[6:7], 0, v[140:141]
	s_nop 0
	v_add_co_u32_e32 v14, vcc, 0x1b72900, v14
	s_nop 1
	v_addc_co_u32_e32 v15, vcc, 0, v15, vcc
	global_load_dwordx4 v[64:67], v[14:15], off
	global_load_dwordx4 v[68:71], v[14:15], off offset:64
	global_load_dwordx4 v[72:75], v[14:15], off offset:128
	global_load_dwordx4 v[76:79], v[14:15], off offset:192
	global_load_dwordx4 v[80:83], v[14:15], off offset:256
	global_load_dwordx4 v[84:87], v[14:15], off offset:320
	global_load_dwordx4 v[88:91], v[14:15], off offset:384
	global_load_dwordx4 v[92:95], v[14:15], off offset:448
	global_load_dwordx4 v[96:99], v[14:15], off offset:512
	global_load_dwordx4 v[100:103], v[14:15], off offset:576
	global_load_dwordx4 v[104:107], v[14:15], off offset:640
	global_load_dwordx4 v[108:111], v[14:15], off offset:704
	global_load_dwordx4 v[112:115], v[14:15], off offset:768
	global_load_dwordx4 v[116:119], v[14:15], off offset:832
	global_load_dwordx4 v[120:123], v[14:15], off offset:896
	global_load_dwordx4 v[124:127], v[14:15], off offset:960
	global_load_dwordx4 v[152:155], v[14:15], off offset:1024
	global_load_dwordx4 v[156:159], v[14:15], off offset:1088
	global_load_dwordx4 v[160:163], v[14:15], off offset:1152
	global_load_dwordx4 v[164:167], v[14:15], off offset:1216
	global_load_dwordx4 v[168:171], v[14:15], off offset:1280
	global_load_dwordx4 v[172:175], v[14:15], off offset:1344
	global_load_dwordx4 v[176:179], v[14:15], off offset:1408
	global_load_dwordx4 v[180:183], v[14:15], off offset:1472
	global_load_dwordx4 v[184:187], v[14:15], off offset:1536
	global_load_dwordx4 v[188:191], v[14:15], off offset:1600
	global_load_dwordx4 v[192:195], v[14:15], off offset:1664
	global_load_dwordx4 v[196:199], v[14:15], off offset:1728
	global_load_dwordx4 v[204:207], v[14:15], off offset:1792
	global_load_dwordx4 v[208:211], v[14:15], off offset:1856
	global_load_dwordx4 v[212:215], v[14:15], off offset:1920
	global_load_dwordx4 v[216:219], v[14:15], off offset:1984
	ds_read_b128 v[228:231], v61
	ds_read_b128 v[232:235], v61 offset:1024
	ds_read_b128 v[236:239], v61 offset:2048
	ds_read_b128 v[240:243], v61 offset:3072
	s_waitcnt vmcnt(31) lgkmcnt(3)
	v_mfma_f32_16x16x32_f16 v[0:3], v[228:231], v[64:67], v[0:3]
	ds_read_b128 v[244:247], v61 offset:4096
	s_waitcnt vmcnt(30) lgkmcnt(3)
	v_mfma_f32_16x16x32_f16 v[0:3], v[232:235], v[68:71], v[0:3]
	ds_read_b128 v[248:251], v61 offset:5120
	s_waitcnt vmcnt(29) lgkmcnt(3)
	v_mfma_f32_16x16x32_f16 v[0:3], v[236:239], v[72:75], v[0:3]
	ds_read_b128 v[228:231], v61 offset:6144
	s_waitcnt vmcnt(28) lgkmcnt(3)
	v_mfma_f32_16x16x32_f16 v[0:3], v[240:243], v[76:79], v[0:3]
	ds_read_b128 v[232:235], v61 offset:7168
	s_waitcnt vmcnt(27) lgkmcnt(3)
	v_mfma_f32_16x16x32_f16 v[0:3], v[244:247], v[80:83], v[0:3]
	ds_read_b128 v[236:239], v61 offset:8192
	s_waitcnt vmcnt(26) lgkmcnt(3)
	v_mfma_f32_16x16x32_f16 v[0:3], v[248:251], v[84:87], v[0:3]
	ds_read_b128 v[240:243], v61 offset:9216
	s_waitcnt vmcnt(25) lgkmcnt(3)
	v_mfma_f32_16x16x32_f16 v[0:3], v[228:231], v[88:91], v[0:3]
	ds_read_b128 v[244:247], v61 offset:10240
	s_waitcnt vmcnt(24) lgkmcnt(3)
	v_mfma_f32_16x16x32_f16 v[0:3], v[232:235], v[92:95], v[0:3]
	ds_read_b128 v[248:251], v61 offset:11264
	s_waitcnt vmcnt(23) lgkmcnt(3)
	v_mfma_f32_16x16x32_f16 v[0:3], v[236:239], v[96:99], v[0:3]
	ds_read_b128 v[228:231], v61 offset:12288
	s_waitcnt vmcnt(22) lgkmcnt(3)
	v_mfma_f32_16x16x32_f16 v[0:3], v[240:243], v[100:103], v[0:3]
	ds_read_b128 v[232:235], v61 offset:13312
	s_waitcnt vmcnt(21) lgkmcnt(3)
	v_mfma_f32_16x16x32_f16 v[0:3], v[244:247], v[104:107], v[0:3]
	ds_read_b128 v[236:239], v61 offset:14336
	s_waitcnt vmcnt(20) lgkmcnt(3)
	v_mfma_f32_16x16x32_f16 v[0:3], v[248:251], v[108:111], v[0:3]
	ds_read_b128 v[240:243], v61 offset:15360
	s_waitcnt vmcnt(19) lgkmcnt(3)
	v_mfma_f32_16x16x32_f16 v[0:3], v[228:231], v[112:115], v[0:3]
	ds_read_b128 v[244:247], v61 offset:16384
	s_waitcnt vmcnt(18) lgkmcnt(3)
	v_mfma_f32_16x16x32_f16 v[0:3], v[232:235], v[116:119], v[0:3]
	ds_read_b128 v[248:251], v61 offset:17408
	s_waitcnt vmcnt(17) lgkmcnt(3)
	v_mfma_f32_16x16x32_f16 v[0:3], v[236:239], v[120:123], v[0:3]
	ds_read_b128 v[228:231], v61 offset:18432
	s_waitcnt vmcnt(16) lgkmcnt(3)
	v_mfma_f32_16x16x32_f16 v[0:3], v[240:243], v[124:127], v[0:3]
	ds_read_b128 v[232:235], v61 offset:19456
	s_waitcnt vmcnt(15) lgkmcnt(3)
	v_mfma_f32_16x16x32_f16 v[0:3], v[244:247], v[152:155], v[0:3]
	ds_read_b128 v[236:239], v61 offset:20480
	s_waitcnt vmcnt(14) lgkmcnt(3)
	v_mfma_f32_16x16x32_f16 v[0:3], v[248:251], v[156:159], v[0:3]
	ds_read_b128 v[240:243], v61 offset:21504
	s_waitcnt vmcnt(13) lgkmcnt(3)
	v_mfma_f32_16x16x32_f16 v[0:3], v[228:231], v[160:163], v[0:3]
	ds_read_b128 v[244:247], v61 offset:22528
	s_waitcnt vmcnt(12) lgkmcnt(3)
	v_mfma_f32_16x16x32_f16 v[0:3], v[232:235], v[164:167], v[0:3]
	ds_read_b128 v[248:251], v61 offset:23552
	s_waitcnt vmcnt(11) lgkmcnt(3)
	v_mfma_f32_16x16x32_f16 v[0:3], v[236:239], v[168:171], v[0:3]
	ds_read_b128 v[228:231], v61 offset:24576
	s_waitcnt vmcnt(10) lgkmcnt(3)
	v_mfma_f32_16x16x32_f16 v[0:3], v[240:243], v[172:175], v[0:3]
	ds_read_b128 v[232:235], v61 offset:25600
	s_waitcnt vmcnt(9) lgkmcnt(3)
	v_mfma_f32_16x16x32_f16 v[0:3], v[244:247], v[176:179], v[0:3]
	ds_read_b128 v[236:239], v61 offset:26624
	s_waitcnt vmcnt(8) lgkmcnt(3)
	v_mfma_f32_16x16x32_f16 v[0:3], v[248:251], v[180:183], v[0:3]
	ds_read_b128 v[240:243], v61 offset:27648
	s_waitcnt vmcnt(7) lgkmcnt(3)
	v_mfma_f32_16x16x32_f16 v[0:3], v[228:231], v[184:187], v[0:3]
	ds_read_b128 v[244:247], v61 offset:28672
	s_waitcnt vmcnt(6) lgkmcnt(3)
	v_mfma_f32_16x16x32_f16 v[0:3], v[232:235], v[188:191], v[0:3]
	ds_read_b128 v[248:251], v61 offset:29696
	s_waitcnt vmcnt(5) lgkmcnt(3)
	v_mfma_f32_16x16x32_f16 v[0:3], v[236:239], v[192:195], v[0:3]
	ds_read_b128 v[228:231], v61 offset:30720
	s_waitcnt vmcnt(4) lgkmcnt(3)
	v_mfma_f32_16x16x32_f16 v[0:3], v[240:243], v[196:199], v[0:3]
	ds_read_b128 v[232:235], v61 offset:31744
	s_waitcnt vmcnt(3) lgkmcnt(3)
	v_mfma_f32_16x16x32_f16 v[0:3], v[244:247], v[204:207], v[0:3]
	s_waitcnt vmcnt(2) lgkmcnt(2)
	v_mfma_f32_16x16x32_f16 v[0:3], v[248:251], v[208:211], v[0:3]
	s_waitcnt vmcnt(1) lgkmcnt(1)
	v_mfma_f32_16x16x32_f16 v[0:3], v[228:231], v[212:215], v[0:3]
	s_waitcnt vmcnt(0) lgkmcnt(0)
	v_mfma_f32_16x16x32_f16 v[0:3], v[232:235], v[216:219], v[0:3]
	s_branch .Lsk1_done

; template <int MODE>
; __device__ __forceinline__ void skinny(const Params& p, const h16* A, int lda, int row0, int nrt, const h16* Bt, int K, int nct) {
;     ...
;         const int row = row0 + rt * 16 + fr, col = ct * 16 + fq * 4;
;         if (MODE == SK_GATES) {
;             const float* bi = p.in[12]; const float* bf = p.in[13];
;             f32x4 o;
; #pragma unroll
;             for (int r = 0; r < 4; ++r) { const int cc = col + r; o[r] = acc[r] + (cc < 8 ? bi[cc] : bf[cc - 8]); }
;             *(f32x4*)((float*)(ws + OFF_GATES) + (size_t)row * 16 + col) = o;
.Lsk1_done:
	v_or_b32_e32 v6, v12, v138
	v_ashrrev_i32_e32 v7, 31, v6
	v_lshlrev_b64 v[8:9], 2, v[6:7]
	v_mov_b32_e32 v7, v141
	v_lshl_add_u64 v[14:15], v[6:7], 2, s[18:19]
	v_lshl_add_u64 v[12:13], s[16:17], 0, v[8:9]
	v_lshl_add_u64 v[16:17], v[14:15], 0, s[24:25]
	v_cmp_gt_i32_e32 vcc, 8, v6
	v_or_b32_e32 v7, 1, v6
	v_lshl_add_u64 v[18:19], v[12:13], 0, 4
	v_cndmask_b32_e32 v17, v17, v13, vcc
	v_cndmask_b32_e32 v16, v16, v12, vcc
	v_lshl_add_u64 v[20:21], v[14:15], 0, s[26:27]
	v_cmp_gt_i32_e32 vcc, 8, v7
	v_or_b32_e32 v7, 2, v6
	global_load_dword v16, v[16:17], off
	v_cndmask_b32_e32 v19, v21, v19, vcc
	v_cndmask_b32_e32 v18, v20, v18, vcc
	v_lshl_add_u64 v[20:21], v[12:13], 0, 8
	v_lshl_add_u64 v[22:23], v[14:15], 0, s[28:29]
	v_cmp_gt_i32_e32 vcc, 8, v7
	v_or_b32_e32 v17, 3, v6
	v_lshl_add_u64 v[6:7], v[12:13], 0, 12
	v_cndmask_b32_e32 v21, v23, v21, vcc
	v_cndmask_b32_e32 v20, v22, v20, vcc
	v_lshl_add_u64 v[12:13], v[14:15], 0, s[30:31]
	v_cmp_gt_i32_e32 vcc, 8, v17
	global_load_dword v20, v[20:21], off
	v_lshlrev_b64 v[4:5], 6, v[4:5]
	v_cndmask_b32_e32 v7, v13, v7, vcc
	v_cndmask_b32_e32 v6, v12, v6, vcc
	global_load_dword v21, v[6:7], off
	global_load_dword v17, v[18:19], off
	v_add_u32_e32 v11, v56, v11
	v_lshl_add_u64 v[4:5], s[6:7], 0, v[4:5]
	v_cmp_le_i32_e32 vcc, v55, v11
	v_lshl_add_u64 v[4:5], v[4:5], 0, v[8:9]
	s_or_b64 s[8:9], vcc, s[8:9]
	s_waitcnt vmcnt(0)
	v_pk_add_f32 v[2:3], v[2:3], v[20:21]
	v_pk_add_f32 v[0:1], v[0:1], v[16:17]
	global_store_dwordx4 v[4:5], v[0:3], off
	s_andn2_b64 exec, exec, s[8:9]
	s_cbranch_execnz .LBB0_91
